# nt hint on the read-once f32 x loads of the P6 residual epilogue (on v73)
# baseline (speedup 1.0000x reference)
; __device__ __forceinline__ unsigned pk2(float lo, float hi) { f32x2 v = {lo, hi}; bf16x2_t b = __builtin_convertvector(v, bf16x2_t); return __builtin_bit_cast(unsigned, b); }
;     __device__ __forceinline__ void operator()(const f32x4 (&acc)[2][2][4][2], const Unit& u, int wr, int wc, int fr, int fq) const {
;         const int row0 = u.pm * BM + wr * 64 + fr; const int b = (u.pm * BM) / S;
;         f32x4 gv[2][2];
; #pragma unroll
;         for (int bj = 0; bj < 2; ++bj)
; #pragma unroll
;             for (int n = 0; n < 2; ++n) gv[bj][n] = *(const f32x4*)(gate + (size_t)b * 6144 + u.pn * BM + bj * HALF + wc * 32 + 8 * fq + 4 * n);
; #pragma unroll
;         for (int ai = 0; ai < 2; ++ai)
; #pragma unroll
;             for (int m = 0; m < 4; ++m) { const size_t off = (size_t)(row0 + ai * HALF + m * 16) * D + u.pn * BM + wc * 32 + 8 * fq;
; #pragma unroll
;                 for (int bj = 0; bj < 2; ++bj) { const size_t o = off + bj * HALF; f32x4 b0, b1;
;                     if (BASE_BF16) { const u32x4 r = *(const u32x4*)((const bf16_t*)base + o);
;                         b0 = (f32x4){__uint_as_float(r.x << 16), __uint_as_float(r.x & 0xffff0000u), __uint_as_float(r.y << 16), __uint_as_float(r.y & 0xffff0000u)};
;                         b1 = (f32x4){__uint_as_float(r.z << 16), __uint_as_float(r.z & 0xffff0000u), __uint_as_float(r.w << 16), __uint_as_float(r.w & 0xffff0000u)}; }
;                     else { b0 = *(const f32x4*)((const float*)base + o); b1 = *(const f32x4*)((const float*)base + o + 4); }
;                     const f32x4 v0 = b0 + gv[bj][0] * acc[ai][bj][m][0], v1 = b1 + gv[bj][1] * acc[ai][bj][m][1];
;                     u32x4 w; w.x = pk2(v0[0], v0[1]); w.y = pk2(v0[2], v0[3]); w.z = pk2(v1[0], v1[1]); w.w = pk2(v1[2], v1[3]);
;                     *(u32x4*)(out + o) = w; } }
.LBB0_920:
	s_ashr_i32 s27, s34, 31
	s_lshr_b32 s27, s27, 29
	s_add_i32 s27, s34, s27
	s_lshl_b32 s25, s34, 8
	s_ashr_i32 s27, s27, 3
	s_add_i32 s25, s25, s54
	s_mul_hi_i32 s34, s27, 0x6000
	s_mulk_i32 s27, 0x6000
	s_add_u32 s27, s49, s27
	s_addc_u32 s34, s51, s34
	s_lshl_b32 s36, s62, 8
	s_ashr_i32 s37, s36, 31
	s_lshl_b64 s[38:39], s[36:37], 2
	s_add_u32 s27, s27, s38
	v_mbcnt_lo_u32_b32 v130, -1, 0
	v_mbcnt_hi_u32_b32 v130, -1, v130
	s_addc_u32 s34, s34, s39
	v_ashrrev_i32_e32 v128, 1, v130
	s_add_u32 s38, s27, s60
	v_and_b32_e32 v128, -8, v128
	v_and_or_b32 v174, v130, 15, s25
	s_addc_u32 s39, s34, 0
	v_ashrrev_i32_e32 v129, 31, v128
	s_or_b64 s[36:37], s[36:37], s[8:9]
	v_ashrrev_i32_e32 v175, 31, v174
	v_lshl_add_u64 v[132:133], v[128:129], 2, s[38:39]
	v_lshl_add_u64 v[176:177], s[36:37], 0, v[128:129]
	v_lshlrev_b64 v[128:129], 10, v[174:175]
	v_lshl_add_u64 v[160:161], v[176:177], 0, v[128:129]
	v_lshl_add_u64 v[178:179], v[160:161], 2, s[6:7]
	global_load_dwordx4 v[140:143], v[132:133], off
	global_load_dwordx4 v[136:139], v[132:133], off offset:16
	global_load_dwordx4 v[128:131], v[132:133], off offset:528
	s_nop 0
	global_load_dwordx4 v[132:135], v[132:133], off offset:512
	v_lshl_add_u64 v[180:181], v[160:161], 1, s[44:45]
	s_andn2_b64 vcc, exec, s[4:5]
	s_mov_b64 s[4:5], -1
	global_load_dwordx4 v[214:217], v[178:179], off nt
	global_load_dwordx4 v[218:221], v[178:179], off offset:16 nt
	global_load_dwordx4 v[222:225], v[178:179], off offset:512 nt
	global_load_dwordx4 v[226:229], v[178:179], off offset:528 nt
	s_mov_b64 s[98:99], 0x10000
	v_lshl_add_u64 v[246:247], v[178:179], 0, s[98:99]
	global_load_dwordx4 v[230:233], v[246:247], off nt
	global_load_dwordx4 v[234:237], v[246:247], off offset:16 nt
	s_waitcnt vmcnt(4) lgkmcnt(0)
	v_pk_fma_f32 v[126:127], v[126:127], v[142:143], v[216:217]
	v_pk_fma_f32 v[124:125], v[124:125], v[140:141], v[214:215]
	v_pk_fma_f32 v[166:167], v[122:123], v[138:139], v[220:221]
	v_pk_fma_f32 v[122:123], v[120:121], v[136:137], v[218:219]
	v_cvt_pk_bf16_f32 v120, v124, v125
	v_cvt_pk_bf16_f32 v121, v126, v127
	v_cvt_pk_bf16_f32 v122, v122, v123
	v_cvt_pk_bf16_f32 v123, v166, v167
	global_store_dwordx4 v[180:181], v[120:123], off
	s_mov_b64 s[98:99], 0x10000
	v_lshl_add_u64 v[246:247], v[178:179], 0, s[98:99]
	global_load_dwordx4 v[238:241], v[246:247], off offset:512 nt
	global_load_dwordx4 v[242:245], v[246:247], off offset:528 nt
	s_nop 0
	v_or_b32_e32 v166, 16, v174
	v_ashrrev_i32_e32 v167, 31, v166
	v_lshlrev_b64 v[166:167], 10, v[166:167]
	v_lshl_add_u64 v[166:167], v[166:167], 0, v[176:177]
	v_lshl_add_u64 v[168:169], v[166:167], 2, s[6:7]
	s_waitcnt vmcnt(5)
	v_pk_fma_f32 v[118:119], v[118:119], v[134:135], v[224:225]
	v_pk_fma_f32 v[116:117], v[116:117], v[132:133], v[222:223]
	v_pk_fma_f32 v[120:121], v[114:115], v[130:131], v[228:229]
	v_pk_fma_f32 v[114:115], v[112:113], v[128:129], v[226:227]
	v_cvt_pk_bf16_f32 v112, v116, v117
	v_cvt_pk_bf16_f32 v113, v118, v119
	v_cvt_pk_bf16_f32 v114, v114, v115
	v_cvt_pk_bf16_f32 v115, v120, v121
	global_store_dwordx4 v[180:181], v[112:115], off offset:256
	s_mov_b64 s[98:99], 0x20000
	v_lshl_add_u64 v[246:247], v[178:179], 0, s[98:99]
	global_load_dwordx4 v[214:217], v[246:247], off nt
	global_load_dwordx4 v[218:221], v[246:247], off offset:16 nt
	s_nop 0
	v_lshl_add_u64 v[120:121], v[166:167], 1, s[44:45]
	s_waitcnt vmcnt(6)
	v_pk_fma_f32 v[110:111], v[110:111], v[142:143], v[232:233]
	v_pk_fma_f32 v[108:109], v[108:109], v[140:141], v[230:231]
	v_pk_fma_f32 v[112:113], v[106:107], v[138:139], v[236:237]
	v_pk_fma_f32 v[106:107], v[104:105], v[136:137], v[234:235]
	v_cvt_pk_bf16_f32 v104, v108, v109
	v_cvt_pk_bf16_f32 v105, v110, v111
	v_cvt_pk_bf16_f32 v106, v106, v107
	v_cvt_pk_bf16_f32 v107, v112, v113
	global_store_dwordx4 v[120:121], v[104:107], off
	s_mov_b64 s[98:99], 0x20000
	v_lshl_add_u64 v[246:247], v[178:179], 0, s[98:99]
	global_load_dwordx4 v[222:225], v[246:247], off offset:512 nt
	global_load_dwordx4 v[226:229], v[246:247], off offset:528 nt
	s_nop 0
	v_or_b32_e32 v112, 32, v174
	v_ashrrev_i32_e32 v113, 31, v112
	v_lshlrev_b64 v[112:113], 10, v[112:113]
	v_lshl_add_u64 v[112:113], v[112:113], 0, v[176:177]
	v_lshl_add_u64 v[114:115], v[112:113], 2, s[6:7]
	s_waitcnt vmcnt(6)
	v_pk_fma_f32 v[102:103], v[102:103], v[134:135], v[240:241]
	v_pk_fma_f32 v[100:101], v[100:101], v[132:133], v[238:239]
	v_pk_fma_f32 v[104:105], v[98:99], v[130:131], v[244:245]
	v_pk_fma_f32 v[98:99], v[96:97], v[128:129], v[242:243]
	v_cvt_pk_bf16_f32 v96, v100, v101
	v_cvt_pk_bf16_f32 v97, v102, v103
	v_cvt_pk_bf16_f32 v98, v98, v99
	v_cvt_pk_bf16_f32 v99, v104, v105
	global_store_dwordx4 v[120:121], v[96:99], off offset:256
	s_mov_b64 s[98:99], 0x30000
	v_lshl_add_u64 v[246:247], v[178:179], 0, s[98:99]
	global_load_dwordx4 v[230:233], v[246:247], off nt
	global_load_dwordx4 v[234:237], v[246:247], off offset:16 nt
	s_nop 0
	v_lshl_add_u64 v[104:105], v[112:113], 1, s[44:45]
	s_waitcnt vmcnt(6)
	v_pk_fma_f32 v[94:95], v[94:95], v[142:143], v[216:217]
	v_pk_fma_f32 v[92:93], v[92:93], v[140:141], v[214:215]
	v_pk_fma_f32 v[96:97], v[90:91], v[138:139], v[220:221]
	v_pk_fma_f32 v[90:91], v[88:89], v[136:137], v[218:219]
	v_cvt_pk_bf16_f32 v88, v92, v93
	v_cvt_pk_bf16_f32 v89, v94, v95
	v_cvt_pk_bf16_f32 v90, v90, v91
	v_cvt_pk_bf16_f32 v91, v96, v97
	global_store_dwordx4 v[104:105], v[88:91], off
	s_mov_b64 s[98:99], 0x30000
	v_lshl_add_u64 v[246:247], v[178:179], 0, s[98:99]
	global_load_dwordx4 v[238:241], v[246:247], off offset:512 nt
	global_load_dwordx4 v[242:245], v[246:247], off offset:528 nt
	s_nop 0
	v_or_b32_e32 v96, 48, v174
	v_ashrrev_i32_e32 v97, 31, v96
	v_lshlrev_b64 v[96:97], 10, v[96:97]
	v_lshl_add_u64 v[96:97], v[96:97], 0, v[176:177]
	v_lshl_add_u64 v[98:99], v[96:97], 2, s[6:7]
	s_waitcnt vmcnt(6)
; __device__ __forceinline__ unsigned pk2(float lo, float hi) { f32x2 v = {lo, hi}; bf16x2_t b = __builtin_convertvector(v, bf16x2_t); return __builtin_bit_cast(unsigned, b); }
;     __device__ __forceinline__ void operator()(const f32x4 (&acc)[2][2][4][2], const Unit& u, int wr, int wc, int fr, int fq) const {
;     ...
;             for (int m = 0; m < 4; ++m) { const size_t off = (size_t)(row0 + ai * HALF + m * 16) * D + u.pn * BM + wc * 32 + 8 * fq;
; #pragma unroll
;                 for (int bj = 0; bj < 2; ++bj) { const size_t o = off + bj * HALF; f32x4 b0, b1;
;                     if (BASE_BF16) { const u32x4 r = *(const u32x4*)((const bf16_t*)base + o);
;                         b0 = (f32x4){__uint_as_float(r.x << 16), __uint_as_float(r.x & 0xffff0000u), __uint_as_float(r.y << 16), __uint_as_float(r.y & 0xffff0000u)};
;                         b1 = (f32x4){__uint_as_float(r.z << 16), __uint_as_float(r.z & 0xffff0000u), __uint_as_float(r.w << 16), __uint_as_float(r.w & 0xffff0000u)}; }
;                     else { b0 = *(const f32x4*)((const float*)base + o); b1 = *(const f32x4*)((const float*)base + o + 4); }
;                     const f32x4 v0 = b0 + gv[bj][0] * acc[ai][bj][m][0], v1 = b1 + gv[bj][1] * acc[ai][bj][m][1];
;                     u32x4 w; w.x = pk2(v0[0], v0[1]); w.y = pk2(v0[2], v0[3]); w.z = pk2(v1[0], v1[1]); w.w = pk2(v1[2], v1[3]);
;                     *(u32x4*)(out + o) = w; } }
	v_pk_fma_f32 v[86:87], v[86:87], v[134:135], v[224:225]
	v_pk_fma_f32 v[84:85], v[84:85], v[132:133], v[222:223]
	v_pk_fma_f32 v[88:89], v[82:83], v[130:131], v[228:229]
	v_pk_fma_f32 v[82:83], v[80:81], v[128:129], v[226:227]
	v_cvt_pk_bf16_f32 v80, v84, v85
	v_cvt_pk_bf16_f32 v81, v86, v87
	v_cvt_pk_bf16_f32 v82, v82, v83
	v_cvt_pk_bf16_f32 v83, v88, v89
	global_store_dwordx4 v[104:105], v[80:83], off offset:256
	s_lshl_b64 s[98:99], s[16:17], 2
	v_lshl_add_u64 v[246:247], v[178:179], 0, s[98:99]
	global_load_dwordx4 v[214:217], v[246:247], off nt
	global_load_dwordx4 v[218:221], v[246:247], off offset:16 nt
	s_nop 0
	v_lshl_add_u64 v[88:89], v[96:97], 1, s[44:45]
	s_waitcnt vmcnt(6)
	v_pk_fma_f32 v[78:79], v[78:79], v[142:143], v[232:233]
	v_pk_fma_f32 v[76:77], v[76:77], v[140:141], v[230:231]
	v_pk_fma_f32 v[80:81], v[74:75], v[138:139], v[236:237]
	v_pk_fma_f32 v[74:75], v[72:73], v[136:137], v[234:235]
	v_cvt_pk_bf16_f32 v72, v76, v77
	v_cvt_pk_bf16_f32 v73, v78, v79
	v_cvt_pk_bf16_f32 v74, v74, v75
	v_cvt_pk_bf16_f32 v75, v80, v81
	global_store_dwordx4 v[88:89], v[72:75], off
	s_lshl_b64 s[98:99], s[16:17], 2
	v_lshl_add_u64 v[246:247], v[178:179], 0, s[98:99]
	global_load_dwordx4 v[222:225], v[246:247], off offset:512 nt
	global_load_dwordx4 v[226:229], v[246:247], off offset:528 nt
	s_nop 0
	v_lshl_add_u64 v[80:81], v[160:161], 0, s[16:17]
	v_lshl_add_u64 v[82:83], v[80:81], 2, s[6:7]
	s_waitcnt vmcnt(6)
	v_pk_fma_f32 v[70:71], v[70:71], v[134:135], v[240:241]
	v_pk_fma_f32 v[68:69], v[68:69], v[132:133], v[238:239]
	v_pk_fma_f32 v[72:73], v[66:67], v[130:131], v[244:245]
	v_pk_fma_f32 v[66:67], v[64:65], v[128:129], v[242:243]
	v_cvt_pk_bf16_f32 v64, v68, v69
	v_cvt_pk_bf16_f32 v65, v70, v71
	v_cvt_pk_bf16_f32 v66, v66, v67
	v_cvt_pk_bf16_f32 v67, v72, v73
	global_store_dwordx4 v[88:89], v[64:67], off offset:256
	s_lshl_b64 s[98:99], s[18:19], 2
	v_lshl_add_u64 v[246:247], v[178:179], 0, s[98:99]
	global_load_dwordx4 v[230:233], v[246:247], off nt
	global_load_dwordx4 v[234:237], v[246:247], off offset:16 nt
	s_nop 0
	v_lshl_add_u64 v[72:73], v[80:81], 1, s[44:45]
	s_waitcnt vmcnt(6)
	v_pk_fma_f32 v[62:63], v[62:63], v[142:143], v[216:217]
	v_pk_fma_f32 v[60:61], v[60:61], v[140:141], v[214:215]
	v_pk_fma_f32 v[64:65], v[58:59], v[138:139], v[220:221]
	v_pk_fma_f32 v[58:59], v[56:57], v[136:137], v[218:219]
	v_cvt_pk_bf16_f32 v56, v60, v61
	v_cvt_pk_bf16_f32 v57, v62, v63
	v_cvt_pk_bf16_f32 v58, v58, v59
	v_cvt_pk_bf16_f32 v59, v64, v65
	global_store_dwordx4 v[72:73], v[56:59], off
	s_lshl_b64 s[98:99], s[18:19], 2
	v_lshl_add_u64 v[246:247], v[178:179], 0, s[98:99]
	global_load_dwordx4 v[238:241], v[246:247], off offset:512 nt
	global_load_dwordx4 v[242:245], v[246:247], off offset:528 nt
	s_nop 0
	v_lshl_add_u64 v[64:65], v[160:161], 0, s[18:19]
	v_lshl_add_u64 v[66:67], v[64:65], 2, s[6:7]
	s_waitcnt vmcnt(6)
	v_pk_fma_f32 v[54:55], v[54:55], v[134:135], v[224:225]
	v_pk_fma_f32 v[52:53], v[52:53], v[132:133], v[222:223]
	v_pk_fma_f32 v[56:57], v[50:51], v[130:131], v[228:229]
	v_pk_fma_f32 v[50:51], v[48:49], v[128:129], v[226:227]
	v_cvt_pk_bf16_f32 v48, v52, v53
	v_cvt_pk_bf16_f32 v49, v54, v55
	v_cvt_pk_bf16_f32 v50, v50, v51
	v_cvt_pk_bf16_f32 v51, v56, v57
	global_store_dwordx4 v[72:73], v[48:51], off offset:256
	s_lshl_b64 s[98:99], s[20:21], 2
	v_lshl_add_u64 v[246:247], v[178:179], 0, s[98:99]
	global_load_dwordx4 v[214:217], v[246:247], off nt
	global_load_dwordx4 v[218:221], v[246:247], off offset:16 nt
	s_nop 0
	v_lshl_add_u64 v[56:57], v[64:65], 1, s[44:45]
	s_waitcnt vmcnt(6)
; __device__ __forceinline__ unsigned pk2(float lo, float hi) { f32x2 v = {lo, hi}; bf16x2_t b = __builtin_convertvector(v, bf16x2_t); return __builtin_bit_cast(unsigned, b); }
; #define PG8_BAR __builtin_amdgcn_s_barrier()
; template <class Epi, bool ALIGN_EPI, int K, int LDA, int LDB>
; __device__ __forceinline__ void gemm_phase(LAS unsigned char* lds, const int wid, const Gemm g, const StaticOrder& S, const Epi& E) {
;     ...
;         if (!has_next) break;
; #pragma unroll
;         for (int a = 0; a < 2; ++a)
; #pragma unroll
;             for (int b = 0; b < 2; ++b)
; #pragma unroll
;                 for (int m = 0; m < 4; ++m)
; #pragma unroll
;                     for (int n = 0; n < 2; ++n) acc[a][b][m][n] = (f32x4){0.f, 0.f, 0.f, 0.f};
;         cur = nxt; cA = nA; cB = nB; ++ui;
;         if constexpr (ALIGN_EPI) { if (wr == 1) PG8_BAR; }
;     __device__ __forceinline__ void operator()(const f32x4 (&acc)[2][2][4][2], const Unit& u, int wr, int wc, int fr, int fq) const {
;     ...
;             for (int m = 0; m < 4; ++m) { const size_t off = (size_t)(row0 + ai * HALF + m * 16) * D + u.pn * BM + wc * 32 + 8 * fq;
; #pragma unroll
;                 for (int bj = 0; bj < 2; ++bj) { const size_t o = off + bj * HALF; f32x4 b0, b1;
;                     if (BASE_BF16) { const u32x4 r = *(const u32x4*)((const bf16_t*)base + o);
;                         b0 = (f32x4){__uint_as_float(r.x << 16), __uint_as_float(r.x & 0xffff0000u), __uint_as_float(r.y << 16), __uint_as_float(r.y & 0xffff0000u)};
;                         b1 = (f32x4){__uint_as_float(r.z << 16), __uint_as_float(r.z & 0xffff0000u), __uint_as_float(r.w << 16), __uint_as_float(r.w & 0xffff0000u)}; }
;                     else { b0 = *(const f32x4*)((const float*)base + o); b1 = *(const f32x4*)((const float*)base + o + 4); }
;                     const f32x4 v0 = b0 + gv[bj][0] * acc[ai][bj][m][0], v1 = b1 + gv[bj][1] * acc[ai][bj][m][1];
;                     u32x4 w; w.x = pk2(v0[0], v0[1]); w.y = pk2(v0[2], v0[3]); w.z = pk2(v1[0], v1[1]); w.w = pk2(v1[2], v1[3]);
;                     *(u32x4*)(out + o) = w; } }
	v_pk_fma_f32 v[46:47], v[46:47], v[142:143], v[232:233]
	v_pk_fma_f32 v[44:45], v[44:45], v[140:141], v[230:231]
	v_pk_fma_f32 v[48:49], v[42:43], v[138:139], v[236:237]
	v_pk_fma_f32 v[42:43], v[40:41], v[136:137], v[234:235]
	v_cvt_pk_bf16_f32 v40, v44, v45
	v_cvt_pk_bf16_f32 v41, v46, v47
	v_cvt_pk_bf16_f32 v42, v42, v43
	v_cvt_pk_bf16_f32 v43, v48, v49
	global_store_dwordx4 v[56:57], v[40:43], off
	s_lshl_b64 s[98:99], s[20:21], 2
	v_lshl_add_u64 v[246:247], v[178:179], 0, s[98:99]
	global_load_dwordx4 v[222:225], v[246:247], off offset:512 nt
	global_load_dwordx4 v[226:229], v[246:247], off offset:528 nt
	s_nop 0
	v_lshl_add_u64 v[48:49], v[160:161], 0, s[20:21]
	v_lshl_add_u64 v[50:51], v[48:49], 2, s[6:7]
	s_waitcnt vmcnt(6)
	v_pk_fma_f32 v[38:39], v[38:39], v[134:135], v[240:241]
	v_pk_fma_f32 v[36:37], v[36:37], v[132:133], v[238:239]
	v_pk_fma_f32 v[40:41], v[34:35], v[130:131], v[244:245]
	v_pk_fma_f32 v[34:35], v[32:33], v[128:129], v[242:243]
	v_cvt_pk_bf16_f32 v32, v36, v37
	v_cvt_pk_bf16_f32 v33, v38, v39
	v_cvt_pk_bf16_f32 v34, v34, v35
	v_cvt_pk_bf16_f32 v35, v40, v41
	global_store_dwordx4 v[56:57], v[32:35], off offset:256
	s_lshl_b64 s[98:99], s[22:23], 2
	v_lshl_add_u64 v[246:247], v[178:179], 0, s[98:99]
	global_load_dwordx4 v[230:233], v[246:247], off nt
	global_load_dwordx4 v[234:237], v[246:247], off offset:16 nt
	s_nop 0
	v_lshl_add_u64 v[40:41], v[48:49], 1, s[44:45]
	s_waitcnt vmcnt(6)
	v_pk_fma_f32 v[30:31], v[30:31], v[142:143], v[216:217]
	v_pk_fma_f32 v[28:29], v[28:29], v[140:141], v[214:215]
	v_pk_fma_f32 v[32:33], v[26:27], v[138:139], v[220:221]
	v_pk_fma_f32 v[26:27], v[24:25], v[136:137], v[218:219]
	v_cvt_pk_bf16_f32 v24, v28, v29
	v_cvt_pk_bf16_f32 v25, v30, v31
	v_cvt_pk_bf16_f32 v26, v26, v27
	v_cvt_pk_bf16_f32 v27, v32, v33
	global_store_dwordx4 v[40:41], v[24:27], off
	s_lshl_b64 s[98:99], s[22:23], 2
	v_lshl_add_u64 v[246:247], v[178:179], 0, s[98:99]
	global_load_dwordx4 v[238:241], v[246:247], off offset:512 nt
	global_load_dwordx4 v[242:245], v[246:247], off offset:528 nt
	s_nop 0
	v_lshl_add_u64 v[32:33], v[160:161], 0, s[22:23]
	v_lshl_add_u64 v[34:35], v[32:33], 2, s[6:7]
	s_waitcnt vmcnt(6)
	v_pk_fma_f32 v[22:23], v[22:23], v[134:135], v[224:225]
	v_pk_fma_f32 v[20:21], v[20:21], v[132:133], v[222:223]
	v_pk_fma_f32 v[24:25], v[18:19], v[130:131], v[228:229]
	v_pk_fma_f32 v[18:19], v[16:17], v[128:129], v[226:227]
	v_cvt_pk_bf16_f32 v16, v20, v21
	v_cvt_pk_bf16_f32 v17, v22, v23
	v_cvt_pk_bf16_f32 v18, v18, v19
	v_cvt_pk_bf16_f32 v19, v24, v25
	global_store_dwordx4 v[40:41], v[16:19], off offset:256
	s_nop 0
	v_lshl_add_u64 v[24:25], v[32:33], 1, s[44:45]
	s_waitcnt vmcnt(4)
	v_pk_fma_f32 v[14:15], v[14:15], v[142:143], v[232:233]
	v_pk_fma_f32 v[12:13], v[12:13], v[140:141], v[230:231]
	v_pk_fma_f32 v[16:17], v[10:11], v[138:139], v[236:237]
	v_pk_fma_f32 v[10:11], v[8:9], v[136:137], v[234:235]
	v_cvt_pk_bf16_f32 v8, v12, v13
	v_cvt_pk_bf16_f32 v9, v14, v15
	v_cvt_pk_bf16_f32 v10, v10, v11
	v_cvt_pk_bf16_f32 v11, v16, v17
	global_store_dwordx4 v[24:25], v[8:11], off
	s_nop 0
	s_waitcnt vmcnt(2)
	v_pk_fma_f32 v[6:7], v[6:7], v[134:135], v[240:241]
	v_pk_fma_f32 v[4:5], v[4:5], v[132:133], v[238:239]
	v_pk_fma_f32 v[8:9], v[2:3], v[130:131], v[244:245]
	v_pk_fma_f32 v[2:3], v[0:1], v[128:129], v[242:243]
	v_cvt_pk_bf16_f32 v0, v4, v5
	v_cvt_pk_bf16_f32 v1, v6, v7
	v_cvt_pk_bf16_f32 v2, v2, v3
	v_cvt_pk_bf16_f32 v3, v8, v9
	global_store_dwordx4 v[24:25], v[0:3], off offset:256
	s_cbranch_vccnz .LBB0_909
	s_andn2_b64 vcc, exec, s[10:11]
	s_cbranch_vccnz .LBB0_908
	s_barrier
	s_branch .LBB0_908
